# device-wide barrier: the first workgroup to arrive on each XCD fires an L2 write-back without waiting for it, so the XCD's last arriver has less left to write back
# speedup vs baseline: 1.0021x; 1.0021x over previous
; __device__ __forceinline__ unsigned xb_ld(unsigned* p)              { return __hip_atomic_load(p, __ATOMIC_RELAXED, __HIP_MEMORY_SCOPE_AGENT); }
; __device__ __forceinline__ unsigned xb_add(unsigned* p, unsigned v) { return __hip_atomic_fetch_add(p, v, __ATOMIC_RELAXED, __HIP_MEMORY_SCOPE_AGENT); }
; #define XB_SPIN(cond, bar) do { unsigned _sp = 0; while (cond) { __builtin_amdgcn_s_sleep(1); \
;     if ((++_sp & 255u) == 0u) { if (xb_ld(&(bar)[XB_TMO])) break; if (_sp > XB_SPIN_CAP) { atomicAdd(&(bar)[XB_TMO], 1u); break; } } } } while (0)
; __device__ __forceinline__ void xcd_barrier(const XcdBarrier& b) {
;     ...
;         const unsigned old = xb_add(&bar[XB_XSUB(b.x)], 1u);
;         const unsigned gen = old / nloc;
;         if (old + 1u == (gen + 1u) * nloc) {
;             __builtin_amdgcn_fence(__ATOMIC_RELEASE, "agent");
;             asm volatile("s_waitcnt vmcnt(0)" ::: "memory");
;             const unsigned og = xb_add(&bar[XB_TOP], 1u);
;             const unsigned tg = og / nx;
;             if (og + 1u == (tg + 1u) * nx) xb_add(&bar[XB_TOPGEN], 1u);
;             else XB_SPIN(xb_ld(&bar[XB_TOPGEN]) == tg, bar);
;             __builtin_amdgcn_fence(__ATOMIC_ACQUIRE, "agent");
;             xb_add(&bar[XB_XGEN(b.x)], 1u);
;             asm volatile("s_waitcnt vmcnt(0)" ::: "memory");
;         } else {
;             XB_SPIN(xb_ld(&bar[XB_XGEN(b.x)]) == gen, bar);
.LBB0_92:
	s_or_b64 exec, exec, s[8:9]
	v_cvt_f32_u32_e32 v4, v2
	s_waitcnt vmcnt(0)
	v_readfirstlane_b32 s6, v3
	v_sub_u32_e32 v3, 0, v2
	v_rcp_iflag_f32_e32 v4, v4
	v_add_u32_e32 v5, s6, v1
	v_mul_f32_e32 v4, 0x4f7ffffe, v4
	v_cvt_u32_f32_e32 v4, v4
	v_mul_lo_u32 v1, v3, v4
	v_mul_hi_u32 v1, v4, v1
	v_add_u32_e32 v1, v4, v1
	v_mul_hi_u32 v1, v5, v1
	v_mul_lo_u32 v3, v1, v2
	v_sub_u32_e32 v3, v5, v3
	v_add_u32_e32 v4, 1, v1
	v_cmp_ge_u32_e32 vcc, v3, v2
	s_nop 1
	v_cndmask_b32_e32 v1, v1, v4, vcc
	v_sub_u32_e32 v4, v3, v2
	v_cndmask_b32_e32 v3, v3, v4, vcc
	v_add_u32_e32 v4, 1, v1
	v_cmp_ge_u32_e32 vcc, v3, v2
	v_add_u32_e32 v3, 1, v5
	s_nop 0
	v_cndmask_b32_e32 v1, v1, v4, vcc
	v_mul_lo_u32 v4, v2, v1
	v_add_u32_e32 v2, v4, v2
	v_cmp_ne_u32_e32 vcc, v3, v2
	s_and_saveexec_b64 s[6:7], vcc
	s_xor_b64 s[6:7], exec, s[6:7]
	s_cbranch_execz .LBB0_106
	s_waitcnt lgkmcnt(0)
	v_mov_b32_e32 v0, 0x20000
	ds_read_b32 v0, v0
	v_sub_u32_e32 v4, v2, v5
	s_waitcnt lgkmcnt(0)
	v_cmp_eq_u32_e32 vcc, v4, v0
	s_cbranch_vccz .Lfw_1
	buffer_wbl2 sc1
.Lfw_1:
	s_add_u32 s12, s16, 0x1e03500
	s_addc_u32 s13, s17, 0
	v_mov_b32_e32 v0, 0
	global_load_dword v0, v0, s[12:13] sc1
	s_waitcnt vmcnt(0)
	v_cmp_eq_u32_e32 vcc, v0, v1
	s_and_saveexec_b64 s[8:9], vcc
	s_cbranch_execz .LBB0_105
	s_add_u32 s10, s16, 0x1e00200
	s_addc_u32 s11, s17, 0
	s_mov_b32 s26, 1
	s_mov_b64 s[14:15], 0
	v_mov_b32_e32 v0, 0
	s_branch .LBB0_96

; __device__ __forceinline__ unsigned xb_ld(unsigned* p)              { return __hip_atomic_load(p, __ATOMIC_RELAXED, __HIP_MEMORY_SCOPE_AGENT); }
; #define XB_SPIN(cond, bar) do { unsigned _sp = 0; while (cond) { __builtin_amdgcn_s_sleep(1); \
;     if ((++_sp & 255u) == 0u) { if (xb_ld(&(bar)[XB_TMO])) break; if (_sp > XB_SPIN_CAP) { atomicAdd(&(bar)[XB_TMO], 1u); break; } } } } while (0)
; __device__ __forceinline__ void xcd_barrier(const XcdBarrier& b) {
;     ...
;         } else {
;             XB_SPIN(xb_ld(&bar[XB_XGEN(b.x)]) == gen, bar);
;             __builtin_amdgcn_fence(__ATOMIC_ACQUIRE, "agent");
;             asm volatile("s_waitcnt vmcnt(0)" ::: "memory");
;         }
.Lfw_3:
	s_add_u32 s14, s16, 0x1e03500
	s_addc_u32 s15, s17, 0
	v_mov_b32_e32 v0, 0
	global_load_dword v0, v0, s[14:15] sc1
	s_waitcnt vmcnt(0)
	v_cmp_eq_u32_e32 vcc, v0, v1
	s_and_saveexec_b64 s[8:9], vcc
	s_cbranch_execz .LBB0_332
	s_add_u32 s12, s16, 0x1e00200
	s_addc_u32 s13, s17, 0
	s_mov_b32 s28, 1
	s_mov_b64 s[18:19], 0
	v_mov_b32_e32 v0, 0
	s_branch .LBB0_323

; __device__ __forceinline__ unsigned xb_ld(unsigned* p)              { return __hip_atomic_load(p, __ATOMIC_RELAXED, __HIP_MEMORY_SCOPE_AGENT); }
; __device__ __forceinline__ unsigned xb_add(unsigned* p, unsigned v) { return __hip_atomic_fetch_add(p, v, __ATOMIC_RELAXED, __HIP_MEMORY_SCOPE_AGENT); }
; #define XB_SPIN(cond, bar) do { unsigned _sp = 0; while (cond) { __builtin_amdgcn_s_sleep(1); \
;     if ((++_sp & 255u) == 0u) { if (xb_ld(&(bar)[XB_TMO])) break; if (_sp > XB_SPIN_CAP) { atomicAdd(&(bar)[XB_TMO], 1u); break; } } } } while (0)
; __device__ __forceinline__ void xcd_barrier(const XcdBarrier& b) {
;     ...
;         const unsigned old = xb_add(&bar[XB_XSUB(b.x)], 1u);
;         const unsigned gen = old / nloc;
;         if (old + 1u == (gen + 1u) * nloc) {
;             __builtin_amdgcn_fence(__ATOMIC_RELEASE, "agent");
;             asm volatile("s_waitcnt vmcnt(0)" ::: "memory");
;             const unsigned og = xb_add(&bar[XB_TOP], 1u);
;             const unsigned tg = og / nx;
;             if (og + 1u == (tg + 1u) * nx) xb_add(&bar[XB_TOPGEN], 1u);
;             else XB_SPIN(xb_ld(&bar[XB_TOPGEN]) == tg, bar);
;             __builtin_amdgcn_fence(__ATOMIC_ACQUIRE, "agent");
;             xb_add(&bar[XB_XGEN(b.x)], 1u);
;             asm volatile("s_waitcnt vmcnt(0)" ::: "memory");
;         } else {
;             XB_SPIN(xb_ld(&bar[XB_XGEN(b.x)]) == gen, bar);
.LBB0_549:
	s_or_b64 exec, exec, s[12:13]
	v_cvt_f32_u32_e32 v4, v2
	s_waitcnt vmcnt(0)
	v_readfirstlane_b32 s8, v3
	v_sub_u32_e32 v3, 0, v2
	v_rcp_iflag_f32_e32 v4, v4
	v_add_u32_e32 v5, s8, v1
	v_mul_f32_e32 v4, 0x4f7ffffe, v4
	v_cvt_u32_f32_e32 v4, v4
	v_mul_lo_u32 v1, v3, v4
	v_mul_hi_u32 v1, v4, v1
	v_add_u32_e32 v1, v4, v1
	v_mul_hi_u32 v1, v5, v1
	v_mul_lo_u32 v3, v1, v2
	v_sub_u32_e32 v3, v5, v3
	v_add_u32_e32 v4, 1, v1
	v_cmp_ge_u32_e32 vcc, v3, v2
	s_nop 1
	v_cndmask_b32_e32 v1, v1, v4, vcc
	v_sub_u32_e32 v4, v3, v2
	v_cndmask_b32_e32 v3, v3, v4, vcc
	v_add_u32_e32 v4, 1, v1
	v_cmp_ge_u32_e32 vcc, v3, v2
	v_add_u32_e32 v3, 1, v5
	s_nop 0
	v_cndmask_b32_e32 v1, v1, v4, vcc
	v_mul_lo_u32 v4, v2, v1
	v_add_u32_e32 v2, v4, v2
	v_cmp_ne_u32_e32 vcc, v3, v2
	s_and_saveexec_b64 s[8:9], vcc
	s_xor_b64 s[8:9], exec, s[8:9]
	s_cbranch_execz .LBB0_563
	s_waitcnt lgkmcnt(0)
	v_mov_b32_e32 v0, 0x20000
	ds_read_b32 v0, v0
	v_sub_u32_e32 v4, v2, v5
	s_waitcnt lgkmcnt(0)
	v_cmp_eq_u32_e32 vcc, v4, v0
	s_cbranch_vccz .Lfw_4
	buffer_wbl2 sc1
.Lfw_4:
	s_add_u32 s22, s16, 0x1e03500
	s_addc_u32 s23, s17, 0
	v_mov_b32_e32 v0, 0
	global_load_dword v0, v0, s[22:23] sc1
	s_waitcnt vmcnt(0)
	v_cmp_eq_u32_e32 vcc, v0, v1
	s_and_saveexec_b64 s[12:13], vcc
	s_cbranch_execz .LBB0_562
	s_add_u32 s20, s16, 0x1e00200
	s_addc_u32 s21, s17, 0
	s_mov_b32 s33, 1
	s_mov_b64 s[24:25], 0
	v_mov_b32_e32 v0, 0
	s_branch .LBB0_553

; __device__ __forceinline__ unsigned xb_ld(unsigned* p)              { return __hip_atomic_load(p, __ATOMIC_RELAXED, __HIP_MEMORY_SCOPE_AGENT); }
; #define XB_SPIN(cond, bar) do { unsigned _sp = 0; while (cond) { __builtin_amdgcn_s_sleep(1); \
;     if ((++_sp & 255u) == 0u) { if (xb_ld(&(bar)[XB_TMO])) break; if (_sp > XB_SPIN_CAP) { atomicAdd(&(bar)[XB_TMO], 1u); break; } } } } while (0)
; __device__ __forceinline__ void xcd_barrier(const XcdBarrier& b) {
;     ...
;         } else {
;             XB_SPIN(xb_ld(&bar[XB_XGEN(b.x)]) == gen, bar);
;             __builtin_amdgcn_fence(__ATOMIC_ACQUIRE, "agent");
;             asm volatile("s_waitcnt vmcnt(0)" ::: "memory");
;         }
.Lfw_6:
	s_add_u32 s12, s16, 0x1e03500
	s_addc_u32 s13, s17, 0
	v_mov_b32_e32 v0, 0
	global_load_dword v0, v0, s[12:13] sc1
	s_waitcnt vmcnt(0)
	v_cmp_eq_u32_e32 vcc, v0, v1
	s_and_saveexec_b64 s[8:9], vcc
	s_cbranch_execz .LBB0_714
	s_add_u32 s10, s16, 0x1e00200
	s_addc_u32 s11, s17, 0
	s_mov_b32 s33, 1
	s_mov_b64 s[22:23], 0
	v_mov_b32_e32 v0, 0
	s_branch .LBB0_705

; __device__ __forceinline__ unsigned xb_ld(unsigned* p)              { return __hip_atomic_load(p, __ATOMIC_RELAXED, __HIP_MEMORY_SCOPE_AGENT); }
; #define XB_SPIN(cond, bar) do { unsigned _sp = 0; while (cond) { __builtin_amdgcn_s_sleep(1); \
;     if ((++_sp & 255u) == 0u) { if (xb_ld(&(bar)[XB_TMO])) break; if (_sp > XB_SPIN_CAP) { atomicAdd(&(bar)[XB_TMO], 1u); break; } } } } while (0)
; __device__ __forceinline__ void xcd_barrier(const XcdBarrier& b) {
;     ...
;         } else {
;             XB_SPIN(xb_ld(&bar[XB_XGEN(b.x)]) == gen, bar);
;             __builtin_amdgcn_fence(__ATOMIC_ACQUIRE, "agent");
;             asm volatile("s_waitcnt vmcnt(0)" ::: "memory");
;         }
.Lfw_7:
	s_add_u32 s12, s16, 0x1e03500
	s_addc_u32 s13, s17, 0
	v_mov_b32_e32 v0, 0
	global_load_dword v0, v0, s[12:13] sc1
	s_waitcnt vmcnt(0)
	v_cmp_eq_u32_e32 vcc, v0, v1
	s_and_saveexec_b64 s[8:9], vcc
	s_cbranch_execz .LBB0_795
	s_add_u32 s10, s16, 0x1e00200
	s_addc_u32 s11, s17, 0
	s_mov_b32 s33, 1
	s_mov_b64 s[18:19], 0
	v_mov_b32_e32 v0, 0
	s_branch .LBB0_786

; __device__ __forceinline__ unsigned xb_ld(unsigned* p)              { return __hip_atomic_load(p, __ATOMIC_RELAXED, __HIP_MEMORY_SCOPE_AGENT); }
; __device__ __forceinline__ unsigned xb_add(unsigned* p, unsigned v) { return __hip_atomic_fetch_add(p, v, __ATOMIC_RELAXED, __HIP_MEMORY_SCOPE_AGENT); }
; #define XB_SPIN(cond, bar) do { unsigned _sp = 0; while (cond) { __builtin_amdgcn_s_sleep(1); \
;     if ((++_sp & 255u) == 0u) { if (xb_ld(&(bar)[XB_TMO])) break; if (_sp > XB_SPIN_CAP) { atomicAdd(&(bar)[XB_TMO], 1u); break; } } } } while (0)
; __device__ __forceinline__ void xcd_barrier(const XcdBarrier& b) {
;     ...
;         const unsigned old = xb_add(&bar[XB_XSUB(b.x)], 1u);
;         const unsigned gen = old / nloc;
;         if (old + 1u == (gen + 1u) * nloc) {
;             __builtin_amdgcn_fence(__ATOMIC_RELEASE, "agent");
;             asm volatile("s_waitcnt vmcnt(0)" ::: "memory");
;             const unsigned og = xb_add(&bar[XB_TOP], 1u);
;             const unsigned tg = og / nx;
;             if (og + 1u == (tg + 1u) * nx) xb_add(&bar[XB_TOPGEN], 1u);
;             else XB_SPIN(xb_ld(&bar[XB_TOPGEN]) == tg, bar);
;             __builtin_amdgcn_fence(__ATOMIC_ACQUIRE, "agent");
;             xb_add(&bar[XB_XGEN(b.x)], 1u);
;             asm volatile("s_waitcnt vmcnt(0)" ::: "memory");
;         } else {
;             XB_SPIN(xb_ld(&bar[XB_XGEN(b.x)]) == gen, bar);
.LBB0_954:
	s_or_b64 exec, exec, s[6:7]
	v_cvt_f32_u32_e32 v4, v2
	s_waitcnt vmcnt(0)
	v_readfirstlane_b32 s4, v3
	v_sub_u32_e32 v3, 0, v2
	v_rcp_iflag_f32_e32 v4, v4
	v_add_u32_e32 v5, s4, v1
	v_mul_f32_e32 v4, 0x4f7ffffe, v4
	v_cvt_u32_f32_e32 v4, v4
	v_mul_lo_u32 v1, v3, v4
	v_mul_hi_u32 v1, v4, v1
	v_add_u32_e32 v1, v4, v1
	v_mul_hi_u32 v1, v5, v1
	v_mul_lo_u32 v3, v1, v2
	v_sub_u32_e32 v3, v5, v3
	v_add_u32_e32 v4, 1, v1
	v_cmp_ge_u32_e32 vcc, v3, v2
	s_nop 1
	v_cndmask_b32_e32 v1, v1, v4, vcc
	v_sub_u32_e32 v4, v3, v2
	v_cndmask_b32_e32 v3, v3, v4, vcc
	v_add_u32_e32 v4, 1, v1
	v_cmp_ge_u32_e32 vcc, v3, v2
	v_add_u32_e32 v3, 1, v5
	s_nop 0
	v_cndmask_b32_e32 v1, v1, v4, vcc
	v_mul_lo_u32 v4, v2, v1
	v_add_u32_e32 v2, v4, v2
	v_cmp_ne_u32_e32 vcc, v3, v2
	s_and_saveexec_b64 s[4:5], vcc
	s_xor_b64 s[4:5], exec, s[4:5]
	s_cbranch_execz .LBB0_968
	s_waitcnt lgkmcnt(0)
	v_mov_b32_e32 v0, 0x20000
	ds_read_b32 v0, v0
	v_sub_u32_e32 v4, v2, v5
	s_waitcnt lgkmcnt(0)
	v_cmp_eq_u32_e32 vcc, v4, v0
	s_cbranch_vccz .Lfw_9
	buffer_wbl2 sc1
.Lfw_9:
	s_add_u32 s10, s16, 0x1e03500
	s_addc_u32 s11, s17, 0
	v_mov_b32_e32 v0, 0
	global_load_dword v0, v0, s[10:11] sc1
	s_waitcnt vmcnt(0)
	v_cmp_eq_u32_e32 vcc, v0, v1
	s_and_saveexec_b64 s[6:7], vcc
	s_cbranch_execz .LBB0_967
	s_add_u32 s8, s16, 0x1e00200
	s_addc_u32 s9, s17, 0
	s_mov_b32 s26, 1
	s_mov_b64 s[12:13], 0
	v_mov_b32_e32 v0, 0
	s_branch .LBB0_958
